# seam barrier: poll top generation directly, per-XCD generation add removed; hipcc's full vmcnt wait after the P3/P7 GEMM prologue removed (K-tile 1 stays in flight); deferred SSQ atomics kept
# baseline (speedup 1.0000x reference)
; __device__ __forceinline__ unsigned xb_ld(unsigned* p)              { return __hip_atomic_load(p, __ATOMIC_RELAXED, __HIP_MEMORY_SCOPE_AGENT); }
; __device__ __forceinline__ unsigned xb_add(unsigned* p, unsigned v) { return __hip_atomic_fetch_add(p, v, __ATOMIC_RELAXED, __HIP_MEMORY_SCOPE_AGENT); }
; #define XB_SPIN(cond, bar) do { unsigned _sp = 0; while (cond) { __builtin_amdgcn_s_sleep(1); \
;     if ((++_sp & 255u) == 0u) { if (xb_ld(&(bar)[XB_TMO])) break; if (_sp > XB_SPIN_CAP) { atomicAdd(&(bar)[XB_TMO], 1u); break; } } } } while (0)
; __device__ __forceinline__ void xcd_barrier(unsigned* bar, volatile LAS unsigned* st, bool lead) {
;     ...
;             const unsigned og = xb_add(&bar[XB_TOP], 1u);
;             const unsigned tg = og / nx;
;             if (og + 1u == (tg + 1u) * nx) xb_add(&bar[XB_TOPGEN], 1u);
;             else XB_SPIN(xb_ld(&bar[XB_TOPGEN]) == tg, bar);
;             __builtin_amdgcn_fence(__ATOMIC_ACQUIRE, "agent");
;             xb_add(&bar[XB_XGEN(x)], 1u);
;             asm volatile("s_waitcnt vmcnt(0)" ::: "memory");
.LBB0_258:
	s_or_b64 exec, exec, s[0:1]
	v_mov_b32_e32 v0, s22
	v_add_co_u32_e32 v0, vcc, 0x2000, v0
	v_mov_b32_e32 v1, s3
	s_nop 0
	v_addc_co_u32_e32 v1, vcc, 0, v1, vcc
	v_mov_b32_e32 v2, 1
	s_waitcnt lgkmcnt(0)
	buffer_inv sc1
	s_waitcnt vmcnt(0)

; #define PG8_STAGE(bufoff, gbase, voff) do { _Pragma("unroll") for (int _i = 0; _i < 2; ++_i) \
;         __builtin_amdgcn_global_load_lds((const unsigned*)((const char*)(gbase) + (voff)[_i]), (PG8_LAS unsigned*)(lds + (bufoff) + ldsw + _i * 8192), 16, 0, 0); } while (0)
; #define PG8_WAIT_V(n) asm volatile("s_waitcnt vmcnt(" #n ")" ::: "memory")
; #define PG8_BAR __builtin_amdgcn_s_barrier()
; template <class Epi, class Sched, bool ALIGN_EPI = false, bool SP2 = false>
; __device__ __forceinline__ void gemm_phase(PG8_LAS unsigned char* lds, const Gemm g, const Sched& S, const Epi& E, const int wid) {
;     ...
;         PG8_STAGE(PG8_SB(0, 0), cB, voffB); PG8_STAGE(PG8_SB(0, 1), cB + hsB, voffB); PG8_STAGE(PG8_SA(0, 0), cA, voffA); PG8_STAGE(PG8_SA(0, 1), cA + hsA, voffA);
;         if (wr == 1) PG8_BAR;
;         PG8_WAIT_V(2); PG8_BAR;
;         PG8_STAGE(PG8_SB(1, 0), cB + kstep, voffB); PG8_STAGE(PG8_SA(1, 0), cA + kstep, voffA); PG8_STAGE(PG8_SB(1, 1), cB + hsB + kstep, voffB);
;         PG8_WAIT_V(6); PG8_BAR;
.LBB0_412:
	s_add_u32 s8, s1, 0x10600000
	s_addc_u32 s9, s9, 0
	s_lshl_b32 s40, s10, 6
	s_lshl_b32 s1, s10, 13
	s_lshl_b32 s10, s93, 5
	s_and_b32 s41, s10, 0x60
	s_mov_b64 s[10:11], 0x80
	s_add_i32 m0, s23, 0x18000
	v_lshl_add_u64 v[6:7], v[6:7], 0, s[10:11]
	s_lshr_b32 s14, s41, 3
	s_waitcnt vmcnt(2)
	s_barrier
	global_load_lds_dwordx4 v[6:7], off
	v_lshl_add_u64 v[4:5], v[4:5], 0, s[10:11]
	s_add_i32 m0, s23, 0x1a000
	s_add_i32 s42, s23, 0x8000
	s_add_i32 s43, s23, 0xa000
	global_load_lds_dwordx4 v[4:5], off
	v_lshl_add_u64 v[0:1], v[0:1], 0, s[10:11]
	s_mov_b32 m0, s42
	s_add_u32 s12, s24, 0x80080
	global_load_lds_dwordx4 v[0:1], off
	v_lshl_add_u64 v[0:1], v[2:3], 0, s[10:11]
	s_mov_b32 m0, s43
	s_addc_u32 s13, s25, 0
	global_load_lds_dwordx4 v[0:1], off
	s_add_i32 m0, s23, 0x1c000
	v_lshl_add_u64 v[0:1], s[12:13], 0, v[132:133]
	global_load_lds_dwordx4 v[0:1], off
	v_lshl_add_u64 v[0:1], s[12:13], 0, v[128:129]
	s_add_i32 m0, s23, 0x1e000
	s_sext_i32_i16 s50, s0
	global_load_lds_dwordx4 v[0:1], off
	v_and_b32_e32 v1, 48, v9
	v_lshlrev_b32_e32 v3, 6, v9
	s_movk_i32 s0, 0x3c0
	v_ashrrev_i32_e32 v0, 6, v9
	v_and_or_b32 v1, v3, s0, v1
	v_lshlrev_b32_e32 v3, 2, v9
	v_lshl_add_u32 v2, v0, 10, s1
	v_and_b32_e32 v3, 32, v3
	v_add_lshl_u32 v0, v0, s14, 10
	v_bitop3_b32 v148, v1, v0, v3 bitop3:0xde
	v_lshlrev_b32_e32 v0, 15, v8
	v_and_b32_e32 v0, 0xffff0000, v0
	v_bitop3_b32 v2, v1, v2, v3 bitop3:0xde
	v_lshl_add_u32 v0, v10, 12, v0
	v_and_b32_e32 v1, 1, v8
	v_lshl_or_b32 v0, v1, 6, v0
	v_lshl_add_u32 v136, v11, 1, v0
	v_lshlrev_b32_e32 v0, 15, v12
	v_and_b32_e32 v0, 0xffff0000, v0
	s_waitcnt vmcnt(6)
	s_cmpk_lt_u32 s92, 0x100
	v_lshl_add_u32 v0, v13, 12, v0
	v_and_b32_e32 v1, 1, v12
	s_cselect_b64 s[12:13], -1, 0
	v_lshl_or_b32 v0, v1, 6, v0
	s_add_i32 s47, 0, 0x10000
	s_add_i32 s48, 0, 0x14000
	s_mov_b32 s44, 0
	s_ashr_i32 s45, s70, 31
	s_mov_b32 s46, s70
	v_mov_b32_e32 v137, v133
	v_lshl_add_u32 v138, v14, 1, v0
	v_mov_b32_e32 v139, v133
	v_mov_b64_e32 v[140:141], 0xb00
	v_mov_b64_e32 v[142:143], 0xaff
	v_add_u32_e32 v149, s47, v148
	v_add_u32_e32 v150, s48, v148
	v_add_u32_e32 v151, 0, v2
	s_movk_i32 s49, 0x2c00
	s_barrier
	s_branch .LBB0_415

; #define PG8_STAGE(bufoff, gbase, voff) do { _Pragma("unroll") for (int _i = 0; _i < 2; ++_i) \
;         __builtin_amdgcn_global_load_lds((const unsigned*)((const char*)(gbase) + (voff)[_i]), (PG8_LAS unsigned*)(lds + (bufoff) + ldsw + _i * 8192), 16, 0, 0); } while (0)
; #define PG8_WAIT_V(n) asm volatile("s_waitcnt vmcnt(" #n ")" ::: "memory")
; #define PG8_BAR __builtin_amdgcn_s_barrier()
; template <class Epi, class Sched, bool ALIGN_EPI = false, bool SP2 = false>
; __device__ __forceinline__ void gemm_phase(PG8_LAS unsigned char* lds, const Gemm g, const Sched& S, const Epi& E, const int wid) {
;     ...
;         PG8_STAGE(PG8_SB(0, 0), cB, voffB); PG8_STAGE(PG8_SB(0, 1), cB + hsB, voffB); PG8_STAGE(PG8_SA(0, 0), cA, voffA); PG8_STAGE(PG8_SA(0, 1), cA + hsA, voffA);
;         if (wr == 1) PG8_BAR;
;         PG8_WAIT_V(2); PG8_BAR;
;         PG8_STAGE(PG8_SB(1, 0), cB + kstep, voffB); PG8_STAGE(PG8_SA(1, 0), cA + kstep, voffA); PG8_STAGE(PG8_SB(1, 1), cB + hsB + kstep, voffB);
;         PG8_WAIT_V(6); PG8_BAR;
.LBB0_763:
	s_add_u32 s10, s1, 0x19600000
	s_addc_u32 s11, s4, 0
	s_lshl_b32 s4, s93, 5
	s_mov_b64 s[12:13], 0x80
	s_and_b32 s4, s4, 0x60
	s_add_i32 m0, s40, 0x18000
	v_lshl_add_u64 v[6:7], v[6:7], 0, s[12:13]
	s_lshl_b32 s1, s0, 13
	s_lshr_b32 s17, s4, 3
	s_waitcnt vmcnt(2)
	s_barrier
	global_load_lds_dwordx4 v[6:7], off
	v_lshl_add_u64 v[4:5], v[4:5], 0, s[12:13]
	s_add_i32 m0, s40, 0x1a000
	s_add_i32 s46, s40, 0x8000
	s_add_i32 s47, s40, 0xa000
	global_load_lds_dwordx4 v[4:5], off
	v_lshl_add_u64 v[2:3], v[2:3], 0, s[12:13]
	s_mov_b32 m0, s46
	s_add_u32 s14, s28, 0x30080
	global_load_lds_dwordx4 v[2:3], off
	v_lshl_add_u64 v[0:1], v[0:1], 0, s[12:13]
	s_mov_b32 m0, s47
	s_addc_u32 s15, s29, 0
	global_load_lds_dwordx4 v[0:1], off
	s_add_i32 m0, s40, 0x1c000
	v_lshl_add_u64 v[0:1], s[14:15], 0, v[132:133]
	global_load_lds_dwordx4 v[0:1], off
	v_lshl_add_u64 v[0:1], s[14:15], 0, v[128:129]
	s_add_i32 m0, s40, 0x1e000
	v_and_b32_e32 v2, 48, v8
	global_load_lds_dwordx4 v[0:1], off
	v_and_b32_e32 v0, 15, v8
	v_lshl_or_b32 v144, s0, 6, v0
	v_ashrrev_i32_e32 v1, 6, v8
	v_lshl_or_b32 v0, v0, 6, v2
	v_lshlrev_b32_e32 v2, 2, v8
	v_lshl_add_u32 v3, v1, 10, s1
	v_and_b32_e32 v2, 32, v2
	v_add_lshl_u32 v1, v1, s17, 10
	v_bitop3_b32 v3, v0, v3, v2 bitop3:0xde
	v_bitop3_b32 v145, v0, v1, v2 bitop3:0xde
	v_ashrrev_i32_e32 v0, 2, v8
	v_and_b32_e32 v0, -4, v0
	v_add_u32_e32 v146, s4, v0
	v_lshrrev_b32_e32 v1, 1, v10
	v_mul_lo_u32 v0, v11, s16
	v_mad_u64_u32 v[0:1], s[0:1], v1, s5, v[0:1]
	v_or_b32_e32 v0, v0, v9
	v_add_lshl_u32 v0, v0, v12, 1
	v_mov_b32_e32 v1, v133
	s_mov_b64 s[0:1], 0x600080
	v_lshl_add_u64 v[136:137], v[0:1], 0, s[0:1]
	v_lshrrev_b32_e32 v1, 1, v14
	v_mul_lo_u32 v0, v15, s16
	v_mad_u64_u32 v[0:1], s[4:5], v1, s5, v[0:1]
	s_waitcnt vmcnt(6)
	s_cmpk_lt_u32 s92, 0x100
	v_or_b32_e32 v0, v0, v13
	s_cselect_b64 s[14:15], -1, 0
	v_add_lshl_u32 v0, v0, v16, 1
	v_mov_b32_e32 v1, v133
	s_add_i32 s51, 0, 0x10000
	s_add_i32 s52, 0, 0x14000
	s_mov_b32 s48, 0
	s_ashr_i32 s49, s70, 31
	s_mov_b32 s50, s70
	v_lshl_add_u64 v[138:139], v[0:1], 0, s[0:1]
	v_mov_b64_e32 v[140:141], 0x80
	v_mov_b64_e32 v[142:143], 0x7f
	v_add_u32_e32 v147, s51, v145
	v_add_u32_e32 v148, s52, v145
	v_add_u32_e32 v149, 0, v3
	s_mov_b64 s[16:17], 0x400000
	s_mov_b32 s53, 0x400000
	s_mov_b64 s[18:19], 0x480000
	s_mov_b32 s54, 0x480000
	s_mov_b64 s[20:21], 0x500000
	s_mov_b32 s55, 0x500000
	s_mov_b64 s[22:23], 0x580000
	s_barrier
	s_branch .LBB0_766
